# attention phases only: one static s_setprio 1 for the second workgroup of each CU (block id >= 256) at phase entry, reset to 0 at the phase's closing grid barrier
# baseline (speedup 1.0000x reference)
;   DI const float* x() const { return (const float*)sp[0]; }
; template <int layer, int part>
; DI void phase_mix(const Params& p, int cidx, char* smem, int* s_item) {
;     ...
;   const int nsb = layer == 0 ? 12 : 16;
;   const bool scanner = part != 1 && ((int)gridDim.x != 512 || (int)(blockIdx.x >> 3) < nsb);
;   if (scanner || part != 0) NEXT_ITEM(); else item = 1 << 30;
.LBB0_748:
	s_or_b64 exec, exec, s[4:5]
	v_readlane_b32 s0, v254, 16
	v_readlane_b32 s1, v254, 17
	v_mov_b32_e32 v0, v202
	s_waitcnt lgkmcnt(0)
	s_barrier
	s_cselect_b32 s32, 1, 0
	v_readlane_b32 s98, v254, 0
	s_nop 1
	s_cmp_lt_u32 s98, 0x100
	s_cbranch_scc1 .Lprio_skip_0
	s_setprio 1
.Lprio_skip_0:
	s_cmp_lg_u32 s32, 0
	s_nop 0
	v_cmp_eq_u32_e64 s[6:7], 0, v0
	s_barrier
	s_and_saveexec_b64 s[2:3], s[6:7]
	s_xor_b64 s[2:3], exec, s[2:3]
	s_cbranch_execz .LBB0_752
	s_mov_b64 s[8:9], exec
	v_mbcnt_lo_u32_b32 v0, s8, 0
	v_mbcnt_hi_u32_b32 v0, s9, v0
	v_cmp_eq_u32_e32 vcc, 0, v0
	s_and_saveexec_b64 s[4:5], vcc
	s_cbranch_execz .LBB0_751
	s_bcnt1_i32_b64 s8, s[8:9]
	v_mov_b32_e32 v1, s8
	v_readlane_b32 s8, v255, 5
	v_readlane_b32 s9, v255, 6
	s_nop 4
	global_atomic_add v1, v129, v1, s[8:9] offset:512 sc0

;   DI const float* x() const { return (const float*)sp[0]; }
; __device__ __forceinline__ void xcd_barrier(const XcdBarrier& b) {
;     asm volatile("s_waitcnt vmcnt(0)" ::: "memory");
;     __syncthreads();
;     if (threadIdx.x == 0) {
;         unsigned* bar = b.bar;
;         __builtin_amdgcn_s_waitcnt(0);
;         unsigned nloc = b.st[0], nx = b.st[1];
;         if (nloc == 0u) { xcd_barrier_complete(bar, b.x, nloc, nx); b.st[0] = nloc; b.st[1] = nx; }
.LBB0_771:
	s_mov_b64 s[38:39], s[58:59]
	ds_read_b32 v0, v215
	s_waitcnt vmcnt(0)
	s_waitcnt lgkmcnt(0)
	s_barrier
	s_setprio 0
	v_readfirstlane_b32 s74, v0
	s_mov_b64 s[4:5], exec
	v_readlane_b32 s0, v254, 1
	v_readlane_b32 s1, v254, 2
	s_and_b64 s[0:1], s[4:5], s[0:1]
	s_mov_b64 exec, s[0:1]
	s_cbranch_execz .LBB0_815
	s_waitcnt vmcnt(0) expcnt(0) lgkmcnt(0)
	ds_read_b32 v2, v216
	ds_read_b32 v0, v217
	s_waitcnt lgkmcnt(1)
	v_cmp_ne_u32_e32 vcc, 0, v2
	s_cbranch_vccnz .LBB0_786
	s_add_u32 s0, s38, 0xe36d200
	s_addc_u32 s1, s39, 0
	s_add_u32 s6, s38, 0xe36d400
	s_addc_u32 s7, s39, 0
	s_add_u32 s8, s38, 0xe36d500
	s_addc_u32 s9, s39, 0
	s_add_u32 s10, s38, 0xe36d600
	s_addc_u32 s11, s39, 0
	s_add_u32 s12, s38, 0xe36d700
	s_addc_u32 s13, s39, 0
	s_add_u32 s14, s38, 0xe36d800
	s_addc_u32 s15, s39, 0
	s_add_u32 s16, s38, 0xe36d900
	s_addc_u32 s17, s39, 0
	s_add_u32 s18, s38, 0xe36da00
	s_addc_u32 s19, s39, 0
	s_add_u32 s20, s38, 0xe36db00
	s_addc_u32 s21, s39, 0
	s_add_u32 s22, s38, 0xe36dc00
	s_addc_u32 s23, s39, 0
	s_add_u32 s24, s38, 0xe36dd00
	s_addc_u32 s25, s39, 0
	s_add_u32 s26, s38, 0xe36de00
	s_addc_u32 s27, s39, 0
	s_add_u32 s28, s38, 0xe36df00
	s_addc_u32 s29, s39, 0
	s_add_u32 s30, s38, 0xe36e000
	s_addc_u32 s31, s39, 0
	s_add_u32 s34, s38, 0xe36e100
	s_addc_u32 s35, s39, 0
	s_add_u32 s40, s38, 0xe36e200
	s_addc_u32 s41, s39, 0
	s_add_u32 s42, s38, 0xe36e300
	s_addc_u32 s43, s39, 0
	s_mov_b32 s75, 1
	s_mov_b64 s[44:45], 0
	s_branch .LBB0_776

;   DI const float* x() const { return (const float*)sp[0]; }
; template <int layer, int part>
; DI void phase_mix(const Params& p, int cidx, char* smem, int* s_item) {
;     ...
;   const int nsb = layer == 0 ? 12 : 16;
;   const bool scanner = part != 1 && ((int)gridDim.x != 512 || (int)(blockIdx.x >> 3) < nsb);
;   if (scanner || part != 0) NEXT_ITEM(); else item = 1 << 30;
.LBB0_2062:
	s_or_b64 exec, exec, s[30:31]
	v_readlane_b32 s0, v254, 16
	v_readlane_b32 s1, v254, 17
	v_mov_b32_e32 v0, v202
	s_waitcnt lgkmcnt(0)
	s_barrier
	s_cselect_b32 s32, 1, 0
	v_readlane_b32 s98, v254, 0
	s_nop 1
	s_cmp_lt_u32 s98, 0x100
	s_cbranch_scc1 .Lprio_skip_1
	s_setprio 1
.Lprio_skip_1:
	s_cmp_lg_u32 s32, 0
	s_nop 0
	v_cmp_eq_u32_e64 s[2:3], 0, v0
	s_barrier
	s_and_saveexec_b64 s[4:5], s[2:3]
	s_xor_b64 s[4:5], exec, s[4:5]
	s_cbranch_execz .LBB0_2066
	s_mov_b64 s[8:9], exec
	v_mbcnt_lo_u32_b32 v0, s8, 0
	v_mbcnt_hi_u32_b32 v0, s9, v0
	v_cmp_eq_u32_e32 vcc, 0, v0
	s_and_saveexec_b64 s[6:7], vcc
	s_cbranch_execz .LBB0_2065
	s_bcnt1_i32_b64 s8, s[8:9]
	v_mov_b32_e32 v1, s8
	v_readlane_b32 s8, v254, 27
	v_readlane_b32 s9, v254, 28
	s_nop 4
	global_atomic_add v1, v185, v1, s[8:9] offset:768 sc0

;   DI const float* x() const { return (const float*)sp[0]; }
; __device__ __forceinline__ void xcd_barrier(const XcdBarrier& b) {
;     asm volatile("s_waitcnt vmcnt(0)" ::: "memory");
;     __syncthreads();
;     if (threadIdx.x == 0) {
;         unsigned* bar = b.bar;
;         __builtin_amdgcn_s_waitcnt(0);
;         unsigned nloc = b.st[0], nx = b.st[1];
;         if (nloc == 0u) { xcd_barrier_complete(bar, b.x, nloc, nx); b.st[0] = nloc; b.st[1] = nx; }
.LBB0_2082:
	s_mov_b64 s[34:35], s[58:59]
	v_mov_b32_e32 v0, 0x122c8
	ds_read_b32 v0, v0
	s_waitcnt vmcnt(0)
	s_waitcnt lgkmcnt(0)
	s_barrier
	s_setprio 0
	v_readfirstlane_b32 s42, v0
	s_mov_b64 s[30:31], exec
	v_readlane_b32 s0, v254, 1
	v_readlane_b32 s1, v254, 2
	s_and_b64 s[0:1], s[30:31], s[0:1]
	s_mov_b64 exec, s[0:1]
	s_cbranch_execz .LBB0_2126
	v_mov_b32_e32 v0, 0x122c0
	s_waitcnt vmcnt(0) expcnt(0) lgkmcnt(0)
	ds_read_b32 v2, v0
	v_mov_b32_e32 v0, 0x122c4
	ds_read_b32 v0, v0
	s_waitcnt lgkmcnt(1)
	v_cmp_ne_u32_e32 vcc, 0, v2
	s_cbranch_vccnz .LBB0_2097
	s_add_u32 s0, s34, 0xe36d200
	s_addc_u32 s1, s35, 0
	s_add_u32 s2, s34, 0xe36d400
	s_addc_u32 s3, s35, 0
	s_add_u32 s4, s34, 0xe36d500
	s_addc_u32 s5, s35, 0
	s_add_u32 s6, s34, 0xe36d600
	s_addc_u32 s7, s35, 0
	s_add_u32 s8, s34, 0xe36d700
	s_addc_u32 s9, s35, 0
	s_add_u32 s10, s34, 0xe36d800
	s_addc_u32 s11, s35, 0
	s_add_u32 s12, s34, 0xe36d900
	s_addc_u32 s13, s35, 0
	s_add_u32 s14, s34, 0xe36da00
	s_addc_u32 s15, s35, 0
	s_add_u32 s16, s34, 0xe36db00
	s_addc_u32 s17, s35, 0
	s_add_u32 s18, s34, 0xe36dc00
	s_addc_u32 s19, s35, 0
	s_add_u32 s20, s34, 0xe36dd00
	s_addc_u32 s21, s35, 0
	s_add_u32 s22, s34, 0xe36de00
	s_addc_u32 s23, s35, 0
	s_add_u32 s24, s34, 0xe36df00
	s_addc_u32 s25, s35, 0
	s_add_u32 s26, s34, 0xe36e000
	s_addc_u32 s27, s35, 0
	s_add_u32 s28, s34, 0xe36e100
	s_addc_u32 s29, s35, 0
	s_add_u32 s36, s34, 0xe36e200
	s_addc_u32 s37, s35, 0
	s_add_u32 s38, s34, 0xe36e300
	s_mov_b32 s97, s91
	s_addc_u32 s39, s35, 0
	s_mov_b32 s96, 1
	s_mov_b64 s[54:55], 0
	s_branch .LBB0_2087
